# GEMM K-loop stage loads: scalar base + lane offset addressing, no per-load 64-bit VALU adds
# speedup vs baseline: 1.0249x; 1.0030x over previous
; #define PG8_STAGE(bufoff, gbase, voff) do { _Pragma("unroll") for (int _i = 0; _i < 2; ++_i) \
;         __builtin_amdgcn_global_load_lds((const unsigned*)((const char*)(gbase) + (voff)[_i]), (LAS unsigned*)(lds + (bufoff) + ldsw + _i * 8192), 16, 0, 0); } while (0)
; #define PG8_LDA(dst, b, h) do { _Pragma("unroll") for (int m = 0; m < 4; ++m) _Pragma("unroll") for (int k = 0; k < 2; ++k) dst[m][k] = *(const LAS bf16x8*)(lds + PG8_SA(b, h) + aoff + m * 2048 + k * 1024); } while (0)
; #define PG8_LDB(dst, b, h) do { _Pragma("unroll") for (int n = 0; n < 2; ++n) _Pragma("unroll") for (int k = 0; k < 2; ++k) dst[n][k] = *(const LAS bf16x8*)(lds + PG8_SB(b, h) + boff + n * 2048 + k * 1024); } while (0)
; #define PG8_MMA(ai, bj, At, Bt) do { __builtin_amdgcn_s_setprio(1); _Pragma("unroll") for (int m = 0; m < 4; ++m) _Pragma("unroll") for (int n = 0; n < 2; ++n) _Pragma("unroll") for (int k = 0; k < 2; ++k) \
;         acc[ai][bj][m][n] = __builtin_amdgcn_mfma_f32_16x16x32_bf16(Bt[n][k], At[m][k], acc[ai][bj][m][n], 0, 0, 0); __builtin_amdgcn_s_setprio(0); } while (0)
; #define PG8_WAIT_V(n) asm volatile("s_waitcnt vmcnt(" #n ")" ::: "memory")
; #define PG8_WAIT_L(n) asm volatile("s_waitcnt lgkmcnt(" #n ")" ::: "memory")
; #define PG8_BAR __builtin_amdgcn_s_barrier()
; #define PG8_SCHED __builtin_amdgcn_sched_barrier(0)
; template <class Epi>
; __device__ __forceinline__ void gemm_phase(LAS unsigned char* lds, const Gemm g, const TabSched& S, const Epi& E) {
;     ...
;             const char* a1 = cA + (size_t)(t + 1) * kstep;
;             const char* a2 = last ? nA : cA + (size_t)(t + 2) * kstep; const char* b2 = last ? nB : cB + (size_t)(t + 2) * kstep;
;             const char* a3 = a2 + kstep; const char* b3 = b2 + kstep;
;             PG8_LDB(B0, 0, 0); PG8_LDB(B1, 0, 1); PG8_SCHED; PG8_LDA(At, 0, 0); PG8_STAGE(PG8_SA(1, 1), a1 + hstep, voffA);
;             PG8_WAIT_V(8); PG8_WAIT_L(0); PG8_BAR; PG8_MMA(0, 0, At, B0); PG8_MMA(0, 1, At, B1); PG8_BAR; PG8_SCHED;
;             PG8_LDA(At, 0, 1); PG8_STAGE(PG8_SB(0, 0), b2, voffB); PG8_STAGE(PG8_SB(0, 1), b2 + hstep, voffB); PG8_STAGE(PG8_SA(0, 0), a2, voffA);
;             PG8_WAIT_V(8); PG8_WAIT_L(0); PG8_BAR; PG8_MMA(1, 0, At, B0); PG8_MMA(1, 1, At, B1); PG8_BAR; PG8_SCHED;
.LBB0_417:
	s_add_i32 s50, s40, 2
	s_add_u32 s51, s26, 0x80
	s_addc_u32 s41, s27, 0
	s_add_i32 s74, 0, 0x10000
	s_cmp_eq_u32 s47, s40
	s_cselect_b32 s41, s19, s41
	s_cselect_b32 s40, s42, s51
	s_cselect_b32 s73, s43, s49
	s_cselect_b32 s72, s46, s48
	s_add_i32 s51, 0, 0x14000
	v_add_u32_e32 v166, s74, v178
	v_add_u32_e32 v188, s51, v178
	ds_read_b128 v[136:139], v166
	ds_read_b128 v[140:143], v166 offset:1024
	ds_read_b128 v[162:165], v166 offset:2048
	ds_read_b128 v[166:169], v166 offset:3072
	ds_read_b128 v[170:173], v188
	ds_read_b128 v[174:177], v188 offset:1024
	ds_read_b128 v[184:187], v188 offset:2048
	ds_read_b128 v[188:191], v188 offset:3072
	s_add_u32 s76, s26, s36
	s_addc_u32 s77, s27, 0
	s_add_i32 m0, s54, 0xc000
	ds_read_b128 v[192:195], v183
	ds_read_b128 v[196:199], v183 offset:1024
	ds_read_b128 v[200:203], v183 offset:2048
	ds_read_b128 v[204:207], v183 offset:3072
	ds_read_b128 v[208:211], v183 offset:4096
	ds_read_b128 v[230:233], v183 offset:5120
	ds_read_b128 v[234:237], v183 offset:6144
	ds_read_b128 v[238:241], v183 offset:7168
	global_load_lds_dwordx4 v2, s[76:77]
	s_add_i32 m0, s54, 0xe000
	s_nop 0
	global_load_lds_dwordx4 v146, s[76:77]
	s_waitcnt vmcnt(8)
	s_waitcnt lgkmcnt(0)
	s_barrier
	s_setprio 1
	s_waitcnt lgkmcnt(0)
	v_mfma_f32_16x16x32_bf16 v[132:135], v[136:139], v[192:195], v[132:135]
	v_mfma_f32_16x16x32_bf16 v[128:131], v[162:165], v[192:195], v[128:131]
	v_mfma_f32_16x16x32_bf16 v[124:127], v[136:139], v[200:203], v[124:127]
	v_mfma_f32_16x16x32_bf16 v[120:123], v[162:165], v[200:203], v[120:123]
	v_mfma_f32_16x16x32_bf16 v[116:119], v[136:139], v[208:211], v[116:119]
	v_mfma_f32_16x16x32_bf16 v[112:115], v[162:165], v[208:211], v[112:115]
	v_mfma_f32_16x16x32_bf16 v[108:111], v[136:139], v[234:237], v[108:111]
	v_mfma_f32_16x16x32_bf16 v[104:107], v[162:165], v[234:237], v[104:107]
	v_mfma_f32_16x16x32_bf16 v[132:135], v[140:143], v[196:199], v[132:135]
	v_mfma_f32_16x16x32_bf16 v[128:131], v[166:169], v[196:199], v[128:131]
	v_mfma_f32_16x16x32_bf16 v[124:127], v[140:143], v[204:207], v[124:127]
	v_mfma_f32_16x16x32_bf16 v[120:123], v[166:169], v[204:207], v[120:123]
	v_mfma_f32_16x16x32_bf16 v[116:119], v[140:143], v[230:233], v[116:119]
	v_mfma_f32_16x16x32_bf16 v[112:115], v[166:169], v[230:233], v[112:115]
	v_mfma_f32_16x16x32_bf16 v[108:111], v[140:143], v[238:241], v[108:111]
	v_mfma_f32_16x16x32_bf16 v[104:107], v[166:169], v[238:241], v[104:107]
	s_setprio 0
	s_setprio 1
	v_mfma_f32_16x16x32_bf16 v[100:103], v[170:173], v[192:195], v[100:103]
	v_mfma_f32_16x16x32_bf16 v[96:99], v[184:187], v[192:195], v[96:99]
	v_mfma_f32_16x16x32_bf16 v[92:95], v[170:173], v[200:203], v[92:95]
	v_mfma_f32_16x16x32_bf16 v[88:91], v[184:187], v[200:203], v[88:91]
	v_mfma_f32_16x16x32_bf16 v[84:87], v[170:173], v[208:211], v[84:87]
	v_mfma_f32_16x16x32_bf16 v[80:83], v[184:187], v[208:211], v[80:83]
	v_mfma_f32_16x16x32_bf16 v[76:79], v[170:173], v[234:237], v[76:79]
	v_mfma_f32_16x16x32_bf16 v[72:75], v[184:187], v[234:237], v[72:75]
	v_mfma_f32_16x16x32_bf16 v[100:103], v[174:177], v[196:199], v[100:103]
	v_mfma_f32_16x16x32_bf16 v[96:99], v[188:191], v[196:199], v[96:99]
	v_mfma_f32_16x16x32_bf16 v[92:95], v[174:177], v[204:207], v[92:95]
	v_mfma_f32_16x16x32_bf16 v[88:91], v[188:191], v[204:207], v[88:91]
	v_mfma_f32_16x16x32_bf16 v[84:87], v[174:177], v[230:233], v[84:87]
	v_mfma_f32_16x16x32_bf16 v[80:83], v[188:191], v[230:233], v[80:83]
	v_mfma_f32_16x16x32_bf16 v[76:79], v[174:177], v[238:241], v[76:79]
	v_mfma_f32_16x16x32_bf16 v[72:75], v[188:191], v[238:241], v[72:75]
	s_setprio 0
	s_barrier
	s_add_i32 s74, s74, s53
	s_mov_b32 m0, s74
	s_mov_b32 s78, s72
	s_mov_b32 s79, s73
	ds_read_b128 v[192:195], v183 offset:16384
	ds_read_b128 v[196:199], v183 offset:17408
	ds_read_b128 v[200:203], v183 offset:18432
	ds_read_b128 v[204:207], v183 offset:19456
	ds_read_b128 v[208:211], v183 offset:20480
	ds_read_b128 v[230:233], v183 offset:21504
	ds_read_b128 v[234:237], v183 offset:22528
	ds_read_b128 v[238:241], v183 offset:23552
	global_load_lds_dwordx4 v144, s[72:73]
	s_add_i32 m0, s74, 0x2000
	s_add_u32 s72, s72, s36
	s_addc_u32 s73, s73, 0
	s_add_i32 s51, s51, s53
	global_load_lds_dwordx4 v148, s[78:79]
	s_mov_b32 m0, s51
	s_mov_b32 s82, s72
	s_mov_b32 s83, s73
	global_load_lds_dwordx4 v144, s[72:73]
	s_add_i32 m0, s51, 0x2000
	s_mov_b32 s80, s40
	s_mov_b32 s81, s41
	global_load_lds_dwordx4 v148, s[72:73]
	s_mov_b32 m0, s54
	s_nop 0
	global_load_lds_dwordx4 v2, s[40:41]
	s_mov_b32 m0, s55
	s_nop 0
	global_load_lds_dwordx4 v146, s[40:41]
	s_waitcnt vmcnt(8)
	s_waitcnt lgkmcnt(0)
	s_barrier
; #define PG8_STAGE(bufoff, gbase, voff) do { _Pragma("unroll") for (int _i = 0; _i < 2; ++_i) \
;         __builtin_amdgcn_global_load_lds((const unsigned*)((const char*)(gbase) + (voff)[_i]), (LAS unsigned*)(lds + (bufoff) + ldsw + _i * 8192), 16, 0, 0); } while (0)
; #define PG8_LDA(dst, b, h) do { _Pragma("unroll") for (int m = 0; m < 4; ++m) _Pragma("unroll") for (int k = 0; k < 2; ++k) dst[m][k] = *(const LAS bf16x8*)(lds + PG8_SA(b, h) + aoff + m * 2048 + k * 1024); } while (0)
; #define PG8_LDB(dst, b, h) do { _Pragma("unroll") for (int n = 0; n < 2; ++n) _Pragma("unroll") for (int k = 0; k < 2; ++k) dst[n][k] = *(const LAS bf16x8*)(lds + PG8_SB(b, h) + boff + n * 2048 + k * 1024); } while (0)
; #define PG8_MMA(ai, bj, At, Bt) do { __builtin_amdgcn_s_setprio(1); _Pragma("unroll") for (int m = 0; m < 4; ++m) _Pragma("unroll") for (int n = 0; n < 2; ++n) _Pragma("unroll") for (int k = 0; k < 2; ++k) \
;         acc[ai][bj][m][n] = __builtin_amdgcn_mfma_f32_16x16x32_bf16(Bt[n][k], At[m][k], acc[ai][bj][m][n], 0, 0, 0); __builtin_amdgcn_s_setprio(0); } while (0)
; #define PG8_WAIT_V(n) asm volatile("s_waitcnt vmcnt(" #n ")" ::: "memory")
; #define PG8_WAIT_L(n) asm volatile("s_waitcnt lgkmcnt(" #n ")" ::: "memory")
; #define PG8_BAR __builtin_amdgcn_s_barrier()
; #define PG8_SCHED __builtin_amdgcn_sched_barrier(0)
; template <class Epi>
; __device__ __forceinline__ void gemm_phase(LAS unsigned char* lds, const Gemm g, const TabSched& S, const Epi& E) {
;     ...
;             PG8_WAIT_V(8); PG8_WAIT_L(0); PG8_BAR; PG8_MMA(1, 0, At, B0); PG8_MMA(1, 1, At, B1); PG8_BAR; PG8_SCHED;
;             PG8_LDB(B0, 1, 0); PG8_LDB(B1, 1, 1); PG8_SCHED; PG8_LDA(At, 1, 0); PG8_STAGE(PG8_SA(0, 1), a2 + hstep, voffA);
;             PG8_WAIT_V(8); PG8_WAIT_L(0); PG8_BAR; PG8_MMA(0, 0, At, B0); PG8_MMA(0, 1, At, B1); PG8_BAR; PG8_SCHED;
	s_setprio 1
	s_waitcnt lgkmcnt(0)
	v_mfma_f32_16x16x32_bf16 v[68:71], v[136:139], v[192:195], v[68:71]
	v_mfma_f32_16x16x32_bf16 v[64:67], v[162:165], v[192:195], v[64:67]
	v_mfma_f32_16x16x32_bf16 v[60:63], v[136:139], v[200:203], v[60:63]
	v_mfma_f32_16x16x32_bf16 v[56:59], v[162:165], v[200:203], v[56:59]
	v_mfma_f32_16x16x32_bf16 v[52:55], v[136:139], v[208:211], v[52:55]
	v_mfma_f32_16x16x32_bf16 v[48:51], v[162:165], v[208:211], v[48:51]
	v_mfma_f32_16x16x32_bf16 v[44:47], v[136:139], v[234:237], v[44:47]
	v_mfma_f32_16x16x32_bf16 v[40:43], v[162:165], v[234:237], v[40:43]
	v_mfma_f32_16x16x32_bf16 v[68:71], v[140:143], v[196:199], v[68:71]
	v_mfma_f32_16x16x32_bf16 v[64:67], v[166:169], v[196:199], v[64:67]
	v_mfma_f32_16x16x32_bf16 v[60:63], v[140:143], v[204:207], v[60:63]
	v_mfma_f32_16x16x32_bf16 v[56:59], v[166:169], v[204:207], v[56:59]
	v_mfma_f32_16x16x32_bf16 v[52:55], v[140:143], v[230:233], v[52:55]
	v_mfma_f32_16x16x32_bf16 v[48:51], v[166:169], v[230:233], v[48:51]
	v_mfma_f32_16x16x32_bf16 v[44:47], v[140:143], v[238:241], v[44:47]
	v_mfma_f32_16x16x32_bf16 v[40:43], v[166:169], v[238:241], v[40:43]
	s_setprio 0
	s_setprio 1
	v_mfma_f32_16x16x32_bf16 v[36:39], v[170:173], v[192:195], v[36:39]
	v_mfma_f32_16x16x32_bf16 v[32:35], v[184:187], v[192:195], v[32:35]
	v_mfma_f32_16x16x32_bf16 v[28:31], v[170:173], v[200:203], v[28:31]
	v_mfma_f32_16x16x32_bf16 v[24:27], v[184:187], v[200:203], v[24:27]
	v_mfma_f32_16x16x32_bf16 v[20:23], v[170:173], v[208:211], v[20:23]
	v_mfma_f32_16x16x32_bf16 v[16:19], v[184:187], v[208:211], v[16:19]
	v_mfma_f32_16x16x32_bf16 v[12:15], v[170:173], v[234:237], v[12:15]
	v_mfma_f32_16x16x32_bf16 v[8:11], v[184:187], v[234:237], v[8:11]
	v_mfma_f32_16x16x32_bf16 v[36:39], v[174:177], v[196:199], v[36:39]
	v_mfma_f32_16x16x32_bf16 v[32:35], v[188:191], v[196:199], v[32:35]
	v_mfma_f32_16x16x32_bf16 v[28:31], v[174:177], v[204:207], v[28:31]
	v_mfma_f32_16x16x32_bf16 v[24:27], v[188:191], v[204:207], v[24:27]
	v_mfma_f32_16x16x32_bf16 v[20:23], v[174:177], v[230:233], v[20:23]
	v_mfma_f32_16x16x32_bf16 v[16:19], v[188:191], v[230:233], v[16:19]
	v_mfma_f32_16x16x32_bf16 v[12:15], v[174:177], v[238:241], v[12:15]
	v_mfma_f32_16x16x32_bf16 v[8:11], v[188:191], v[238:241], v[8:11]
	s_setprio 0
	s_barrier
	s_add_i32 s51, 0, 0x18000
	s_add_i32 s72, 0, 0x1c000
	v_add_u32_e32 v166, s51, v178
	v_add_u32_e32 v188, s72, v178
	ds_read_b128 v[136:139], v166
	ds_read_b128 v[140:143], v166 offset:1024
	ds_read_b128 v[162:165], v166 offset:2048
	ds_read_b128 v[166:169], v166 offset:3072
	ds_read_b128 v[170:173], v188
	ds_read_b128 v[174:177], v188 offset:1024
	ds_read_b128 v[184:187], v188 offset:2048
	ds_read_b128 v[188:191], v188 offset:3072
	s_add_u32 s40, s40, s36
	s_addc_u32 s41, s41, 0
	s_mov_b32 m0, s56
	ds_read_b128 v[192:195], v183 offset:32768
	ds_read_b128 v[196:199], v183 offset:33792
	ds_read_b128 v[200:203], v183 offset:34816
	ds_read_b128 v[204:207], v183 offset:35840
	ds_read_b128 v[208:211], v183 offset:36864
	ds_read_b128 v[230:233], v183 offset:37888
	ds_read_b128 v[234:237], v183 offset:38912
	ds_read_b128 v[238:241], v183 offset:39936
	global_load_lds_dwordx4 v2, s[40:41]
	s_mov_b32 m0, s57
	s_nop 0
	global_load_lds_dwordx4 v146, s[40:41]
	s_waitcnt vmcnt(8)
	s_waitcnt lgkmcnt(0)
	s_barrier
	s_setprio 1
	s_waitcnt lgkmcnt(0)
	v_mfma_f32_16x16x32_bf16 v[132:135], v[136:139], v[192:195], v[132:135]
	v_mfma_f32_16x16x32_bf16 v[128:131], v[162:165], v[192:195], v[128:131]
	v_mfma_f32_16x16x32_bf16 v[124:127], v[136:139], v[200:203], v[124:127]
	v_mfma_f32_16x16x32_bf16 v[120:123], v[162:165], v[200:203], v[120:123]
	v_mfma_f32_16x16x32_bf16 v[116:119], v[136:139], v[208:211], v[116:119]
	v_mfma_f32_16x16x32_bf16 v[112:115], v[162:165], v[208:211], v[112:115]
	v_mfma_f32_16x16x32_bf16 v[108:111], v[136:139], v[234:237], v[108:111]
	v_mfma_f32_16x16x32_bf16 v[104:107], v[162:165], v[234:237], v[104:107]
	v_mfma_f32_16x16x32_bf16 v[132:135], v[140:143], v[196:199], v[132:135]
	v_mfma_f32_16x16x32_bf16 v[128:131], v[166:169], v[196:199], v[128:131]
	v_mfma_f32_16x16x32_bf16 v[124:127], v[140:143], v[204:207], v[124:127]
	v_mfma_f32_16x16x32_bf16 v[120:123], v[166:169], v[204:207], v[120:123]
	v_mfma_f32_16x16x32_bf16 v[116:119], v[140:143], v[230:233], v[116:119]
	v_mfma_f32_16x16x32_bf16 v[112:115], v[166:169], v[230:233], v[112:115]
	v_mfma_f32_16x16x32_bf16 v[108:111], v[140:143], v[238:241], v[108:111]
	v_mfma_f32_16x16x32_bf16 v[104:107], v[166:169], v[238:241], v[104:107]
	s_setprio 0
	s_setprio 1
	v_mfma_f32_16x16x32_bf16 v[100:103], v[170:173], v[192:195], v[100:103]
	v_mfma_f32_16x16x32_bf16 v[96:99], v[184:187], v[192:195], v[96:99]
	v_mfma_f32_16x16x32_bf16 v[92:95], v[170:173], v[200:203], v[92:95]
	v_mfma_f32_16x16x32_bf16 v[88:91], v[184:187], v[200:203], v[88:91]
	v_mfma_f32_16x16x32_bf16 v[84:87], v[170:173], v[208:211], v[84:87]
	v_mfma_f32_16x16x32_bf16 v[80:83], v[184:187], v[208:211], v[80:83]
	v_mfma_f32_16x16x32_bf16 v[76:79], v[170:173], v[234:237], v[76:79]
	v_mfma_f32_16x16x32_bf16 v[72:75], v[184:187], v[234:237], v[72:75]
	v_mfma_f32_16x16x32_bf16 v[100:103], v[174:177], v[196:199], v[100:103]
	v_mfma_f32_16x16x32_bf16 v[96:99], v[188:191], v[196:199], v[96:99]
	v_mfma_f32_16x16x32_bf16 v[92:95], v[174:177], v[204:207], v[92:95]
	v_mfma_f32_16x16x32_bf16 v[88:91], v[188:191], v[204:207], v[88:91]
	v_mfma_f32_16x16x32_bf16 v[84:87], v[174:177], v[230:233], v[84:87]
	v_mfma_f32_16x16x32_bf16 v[80:83], v[188:191], v[230:233], v[80:83]
	v_mfma_f32_16x16x32_bf16 v[76:79], v[174:177], v[238:241], v[76:79]
	v_mfma_f32_16x16x32_bf16 v[72:75], v[188:191], v[238:241], v[72:75]
	s_setprio 0
	s_barrier
; #define PG8_STAGE(bufoff, gbase, voff) do { _Pragma("unroll") for (int _i = 0; _i < 2; ++_i) \
;         __builtin_amdgcn_global_load_lds((const unsigned*)((const char*)(gbase) + (voff)[_i]), (LAS unsigned*)(lds + (bufoff) + ldsw + _i * 8192), 16, 0, 0); } while (0)
; #define PG8_LDA(dst, b, h) do { _Pragma("unroll") for (int m = 0; m < 4; ++m) _Pragma("unroll") for (int k = 0; k < 2; ++k) dst[m][k] = *(const LAS bf16x8*)(lds + PG8_SA(b, h) + aoff + m * 2048 + k * 1024); } while (0)
; #define PG8_MMA(ai, bj, At, Bt) do { __builtin_amdgcn_s_setprio(1); _Pragma("unroll") for (int m = 0; m < 4; ++m) _Pragma("unroll") for (int n = 0; n < 2; ++n) _Pragma("unroll") for (int k = 0; k < 2; ++k) \
;         acc[ai][bj][m][n] = __builtin_amdgcn_mfma_f32_16x16x32_bf16(Bt[n][k], At[m][k], acc[ai][bj][m][n], 0, 0, 0); __builtin_amdgcn_s_setprio(0); } while (0)
; #define PG8_WAIT_V(n) asm volatile("s_waitcnt vmcnt(" #n ")" ::: "memory")
; #define PG8_WAIT_L(n) asm volatile("s_waitcnt lgkmcnt(" #n ")" ::: "memory")
; #define PG8_BAR __builtin_amdgcn_s_barrier()
; #define PG8_SCHED __builtin_amdgcn_sched_barrier(0)
; template <class Epi>
; __device__ __forceinline__ void gemm_phase(LAS unsigned char* lds, const Gemm g, const TabSched& S, const Epi& E) {
;     ...
;             PG8_LDA(At, 1, 1); PG8_STAGE(PG8_SB(1, 0), b3, voffB); PG8_STAGE(PG8_SB(1, 1), b3 + hstep, voffB); PG8_STAGE(PG8_SA(1, 0), a3, voffA);
;             PG8_WAIT_V(8); PG8_WAIT_L(0); PG8_BAR; PG8_MMA(1, 0, At, B0); PG8_MMA(1, 1, At, B1); PG8_BAR; PG8_SCHED;
	s_add_i32 s40, s51, s53
	s_add_i32 m0, s40, 0xffffff80
	ds_read_b128 v[192:195], v183 offset:49152
	ds_read_b128 v[196:199], v183 offset:50176
	ds_read_b128 v[200:203], v183 offset:51200
	ds_read_b128 v[204:207], v183 offset:52224
	ds_read_b128 v[208:211], v183 offset:53248
	ds_read_b128 v[230:233], v183 offset:54272
	ds_read_b128 v[234:237], v183 offset:55296
	ds_read_b128 v[238:241], v183 offset:56320
	global_load_lds_dwordx4 v144, s[78:79] offset:128
	s_add_i32 m0, s40, 0x1f80
	s_add_i32 s40, s72, s53
	global_load_lds_dwordx4 v148, s[78:79] offset:128
	s_add_i32 m0, s40, 0xffffff80
	s_nop 0
	global_load_lds_dwordx4 v144, s[82:83] offset:128
	s_add_i32 m0, s40, 0x1f80
	s_nop 0
	global_load_lds_dwordx4 v148, s[82:83] offset:128
	s_add_i32 m0, s58, 0xffffff80
	s_nop 0
	global_load_lds_dwordx4 v2, s[80:81] offset:128
	s_add_i32 m0, s59, 0xffffff80
	s_nop 0
	global_load_lds_dwordx4 v146, s[80:81] offset:128
	s_waitcnt vmcnt(8)
	s_waitcnt lgkmcnt(0)
	s_barrier
	s_setprio 1
	s_waitcnt lgkmcnt(0)
	v_mfma_f32_16x16x32_bf16 v[68:71], v[136:139], v[192:195], v[68:71]
	v_mfma_f32_16x16x32_bf16 v[64:67], v[162:165], v[192:195], v[64:67]
	v_mfma_f32_16x16x32_bf16 v[60:63], v[136:139], v[200:203], v[60:63]
	v_mfma_f32_16x16x32_bf16 v[56:59], v[162:165], v[200:203], v[56:59]
	v_mfma_f32_16x16x32_bf16 v[52:55], v[136:139], v[208:211], v[52:55]
	v_mfma_f32_16x16x32_bf16 v[48:51], v[162:165], v[208:211], v[48:51]
	v_mfma_f32_16x16x32_bf16 v[44:47], v[136:139], v[234:237], v[44:47]
	v_mfma_f32_16x16x32_bf16 v[40:43], v[162:165], v[234:237], v[40:43]
	v_mfma_f32_16x16x32_bf16 v[68:71], v[140:143], v[196:199], v[68:71]
	v_mfma_f32_16x16x32_bf16 v[64:67], v[166:169], v[196:199], v[64:67]
	v_mfma_f32_16x16x32_bf16 v[60:63], v[140:143], v[204:207], v[60:63]
	v_mfma_f32_16x16x32_bf16 v[56:59], v[166:169], v[204:207], v[56:59]
	v_mfma_f32_16x16x32_bf16 v[52:55], v[140:143], v[230:233], v[52:55]
	v_mfma_f32_16x16x32_bf16 v[48:51], v[166:169], v[230:233], v[48:51]
	v_mfma_f32_16x16x32_bf16 v[44:47], v[140:143], v[238:241], v[44:47]
	v_mfma_f32_16x16x32_bf16 v[40:43], v[166:169], v[238:241], v[40:43]
	s_setprio 0
	s_setprio 1
	v_mfma_f32_16x16x32_bf16 v[36:39], v[170:173], v[192:195], v[36:39]
	v_mfma_f32_16x16x32_bf16 v[32:35], v[184:187], v[192:195], v[32:35]
	v_mfma_f32_16x16x32_bf16 v[28:31], v[170:173], v[200:203], v[28:31]
	v_mfma_f32_16x16x32_bf16 v[24:27], v[184:187], v[200:203], v[24:27]
	v_mfma_f32_16x16x32_bf16 v[20:23], v[170:173], v[208:211], v[20:23]
	v_mfma_f32_16x16x32_bf16 v[16:19], v[184:187], v[208:211], v[16:19]
	v_mfma_f32_16x16x32_bf16 v[12:15], v[170:173], v[234:237], v[12:15]
	v_mfma_f32_16x16x32_bf16 v[8:11], v[184:187], v[234:237], v[8:11]
	v_mfma_f32_16x16x32_bf16 v[36:39], v[174:177], v[196:199], v[36:39]
	v_mfma_f32_16x16x32_bf16 v[32:35], v[188:191], v[196:199], v[32:35]
	v_mfma_f32_16x16x32_bf16 v[28:31], v[174:177], v[204:207], v[28:31]
	v_mfma_f32_16x16x32_bf16 v[24:27], v[188:191], v[204:207], v[24:27]
	v_mfma_f32_16x16x32_bf16 v[20:23], v[174:177], v[230:233], v[20:23]
	v_mfma_f32_16x16x32_bf16 v[16:19], v[188:191], v[230:233], v[16:19]
	v_mfma_f32_16x16x32_bf16 v[12:15], v[174:177], v[238:241], v[12:15]
	v_mfma_f32_16x16x32_bf16 v[8:11], v[188:191], v[238:241], v[8:11]
	s_setprio 0
	s_barrier
	s_add_u32 s48, s48, 0x100
	s_addc_u32 s49, s49, 0
	s_add_u32 s26, s26, 0x100
	s_addc_u32 s27, s27, 0
	s_cmp_ge_i32 s50, s13
	s_mov_b32 s40, s50
	s_cbranch_scc0 .LBB0_417
	s_and_b64 vcc, exec, s[6:7]
	s_cbranch_vccz .LBB0_420
